# attention K/V staging split by wave half: waves 0-3 stage K, waves 4-7 stage V^T; tile bases in SGPRs, loop-invariant per-thread offsets (saddr loads), no per-stage address VALU
# speedup vs baseline: 1.0188x; 1.0188x over previous
; #define LAS __attribute__((address_space(3)))
; #define AT_LOAD(st) do { _Pragma("unroll") for (int e = 0; e < 3; ++e) pk[e] = *(const u32x4*)(kbase + (size_t)((st) * 64 + krow[e]) * 768 + kcol[e] * 8); \
;         _Pragma("unroll") for (int e = 0; e < 2; ++e) { const int c = tid + 512 * e; pv[e] = *(const u32x4*)(vbase + (size_t)(c >> 3) * SEQ + (st) * 64 + (c & 7) * 8); } } while (0)
; DI void attn_unit(const Params& p, int b, int h, int qb, LAS unsigned char* lds, int tid, int lane, int wave) {
;     unsigned char* ws = p.ws;
;     const bf16_t* Q = (const bf16_t*)(ws + WS_QR); const bf16_t* KB = (const bf16_t*)(ws + WS_K); const bf16_t* VT = (const bf16_t*)(ws + WS_VT);
;     const bf16_t* Z = (const bf16_t*)(ws + WS_Z); bf16_t* OB = (bf16_t*)(ws + WS_KVR);
;     const int g = wave >> 2, w4 = wave & 3, r = lane & 31, hh = lane >> 5;
;     const int qr0 = qb * 128 + w4 * 32, nst = 2 * (qb + 1);
;     const size_t tokb = (size_t)b * SEQ;
;     bf16x8 qf[12];
;     { const bf16_t* qp = Q + (tokb + qr0 + r) * 768 + h * 192 + 8 * hh;
; #pragma unroll
;       for (int kk = 0; kk < 12; ++kk) qf[kk] = *(const bf16x8*)(qp + 16 * kk); }
;     f32x16 o[4];
; #pragma unroll
;     for (int i = 0; i < 4; ++i)
; #pragma unroll
;         for (int j = 0; j < 16; ++j) o[i][j] = 0.f;
;     float mrow = -INFINITY, lrow = 0.f;
;     const bf16_t* kbase = KB + tokb * 768 + h * 192;
;     const bf16_t* vbase = VT + (size_t)((b * 4 + h) * 128) * SEQ;
;     int krow[3], kcol[3];
; #pragma unroll
;     for (int e = 0; e < 3; ++e) { const int c = tid + 512 * e; krow[e] = c / 24; kcol[e] = c % 24; }
;     u32x4 pk[3], pv[2];
;     ...
;     AT_LOAD(0); AT_WRITE(0);
;     __syncthreads();
.LBB0_426:
	s_mov_b32 s3, s33
	v_mbcnt_lo_u32_b32 v183, -1, 0
	v_mbcnt_hi_u32_b32 v183, -1, v183
	s_mov_b32 s5, 0x2aaaaaab
	v_lshl_add_u32 v14, s3, 6, v183
	v_mul_hi_i32 v0, v14, s5
	v_lshrrev_b32_e32 v2, 31, v0
	v_ashrrev_i32_e32 v0, 2, v0
	v_add_u32_e32 v40, v0, v2
	s_bfe_u32 s4, s73, 0x20006
	s_bfe_u32 s2, s73, 0x20004
	v_mul_lo_u32 v0, v40, 24
	s_waitcnt vmcnt(0)
	v_add_u32_e32 v20, 0x200, v14
	s_lshl_b32 s0, s2, 20
	s_lshl_b32 s1, s4, 22
	v_sub_u32_e32 v41, v14, v0
	v_mul_hi_i32 v0, v20, s5
	s_or_b32 s92, s1, s0
	s_mov_b64 s[0:1], s[50:51]
	v_lshrrev_b32_e32 v2, 31, v0
	v_ashrrev_i32_e32 v0, 2, v0
	s_and_b32 s94, s73, 15
	v_add_u32_e32 v42, v0, v2
	s_xor_b32 s0, s94, 31
	s_and_b32 s20, s3, 3
	v_mul_lo_u32 v0, v42, 24
	s_lshl_b32 s6, s0, 7
	s_lshl_b32 s0, s20, 5
	s_mul_i32 s67, s2, 0xc0
	v_sub_u32_e32 v43, v20, v0
	v_add_u32_e32 v0, 0x400, v14
	s_or_b32 s36, s0, s6
	s_lshl_b32 s66, s4, 12
	s_lshl_b32 s0, s67, 1
	s_ashr_i32 s21, s3, 2
	s_mul_i32 s7, s4, 0x600000
	v_readlane_b32 s1, v254, 52
	v_mul_hi_i32 v2, v0, s5
	s_add_u32 s1, s1, s7
	v_readlane_b32 s4, v254, 53
	v_lshrrev_b32_e32 v3, 31, v2
	v_ashrrev_i32_e32 v2, 2, v2
	s_addc_u32 s4, s4, 0
	v_add_u32_e32 v44, v2, v3
	v_mul_lo_u32 v2, v44, 24
	s_add_u32 s52, s1, s0
	v_sub_u32_e32 v45, v0, v2
	s_addc_u32 s53, s4, 0
	v_lshlrev_b32_e32 v4, 3, v41
	v_lshlrev_b32_e32 v6, 3, v43
	v_mov_b64_e32 v[10:11], s[52:53]
	v_ashrrev_i32_e32 v5, 31, v4
	v_ashrrev_i32_e32 v7, 31, v6
	v_lshlrev_b32_e32 v12, 3, v45
	v_readlane_b32 s1, v254, 50
	v_mad_i64_i32 v[2:3], s[4:5], v40, s76, v[10:11]
	v_lshlrev_b64 v[22:23], 1, v[4:5]
	v_mad_i64_i32 v[4:5], s[4:5], v42, s76, v[10:11]
	v_lshlrev_b64 v[24:25], 1, v[6:7]
	v_ashrrev_i32_e32 v13, 31, v12
	s_add_u32 s74, s1, s92
	v_readlane_b32 s1, v254, 51
	v_lshlrev_b32_e32 v0, 4, v183
	v_ashrrev_i32_e32 v28, 3, v14
	v_lshl_add_u64 v[2:3], v[2:3], 0, v[22:23]
	v_lshl_add_u64 v[6:7], v[4:5], 0, v[24:25]
	v_mad_i64_i32 v[10:11], s[4:5], v44, s76, v[10:11]
	v_lshlrev_b64 v[26:27], 1, v[12:13]
	s_addc_u32 s75, s1, 0
	v_and_b32_e32 v0, 0x70, v0
	v_ashrrev_i32_e32 v29, 31, v28
	v_ashrrev_i32_e32 v32, 3, v20
	global_load_dwordx4 v[2:5], v[2:3], off
	s_nop 0
	global_load_dwordx4 v[6:9], v[6:7], off
	v_lshl_add_u64 v[10:11], v[10:11], 0, v[26:27]
	v_lshl_add_u64 v[18:19], s[74:75], 0, v[0:1]
	v_lshlrev_b64 v[30:31], 13, v[28:29]
	v_ashrrev_i32_e32 v33, 31, v32
	global_load_dwordx4 v[10:13], v[10:11], off
	v_lshl_add_u64 v[14:15], v[18:19], 0, v[30:31]
	v_lshlrev_b64 v[34:35], 13, v[32:33]
	v_and_b32_e32 v29, 31, v183
	v_readlane_b32 s4, v254, 48
	global_load_dwordx4 v[14:17], v[14:15], off
	v_lshl_add_u64 v[18:19], v[18:19], 0, v[34:35]
	v_or_b32_e32 v36, s66, v29
	v_readlane_b32 s5, v254, 49
	global_load_dwordx4 v[18:21], v[18:19], off
	v_ashrrev_i32_e32 v33, 5, v183
	v_or_b32_e32 v202, s36, v36
	v_mov_b64_e32 v[36:37], s[4:5]
	v_mad_u64_u32 v[36:37], s[4:5], v202, s76, v[36:37]
	s_mov_b32 s1, s93
	v_lshlrev_b32_e32 v38, 3, v33
	v_lshl_add_u64 v[36:37], v[36:37], 0, s[0:1]
	v_ashrrev_i32_e32 v39, 31, v38
	v_lshl_add_u64 v[36:37], v[38:39], 1, v[36:37]
	global_load_dwordx4 v[126:129], v[36:37], off
	global_load_dwordx4 v[122:125], v[36:37], off offset:32
	global_load_dwordx4 v[118:121], v[36:37], off offset:64
	global_load_dwordx4 v[114:117], v[36:37], off offset:96
	global_load_dwordx4 v[110:113], v[36:37], off offset:128
	global_load_dwordx4 v[106:109], v[36:37], off offset:160
	global_load_dwordx4 v[102:105], v[36:37], off offset:192
	global_load_dwordx4 v[98:101], v[36:37], off offset:224
	global_load_dwordx4 v[94:97], v[36:37], off offset:256
	global_load_dwordx4 v[90:93], v[36:37], off offset:288
	global_load_dwordx4 v[86:89], v[36:37], off offset:320
	global_load_dwordx4 v[82:85], v[36:37], off offset:352
	v_mul_lo_u32 v207, v40, s77
	v_lshlrev_b32_e32 v208, 4, v41
	v_add3_u32 v36, 0, v207, v208
	v_mul_lo_u32 v209, v42, s77
	v_lshlrev_b32_e32 v210, 4, v43
	v_mul_lo_u32 v211, v44, s77
	v_lshlrev_b32_e32 v212, 4, v45
	s_movk_i32 s0, 0x90
	v_bfe_u32 v222, v0, 4, 1
	v_and_b32_e32 v213, 0x60, v0
	v_lshl_or_b32 v213, v222, 3, v213
	v_mul_lo_u32 v214, v28, s0
	v_mul_lo_u32 v215, v32, s0
	s_lshl_b32 s56, s21, 5
	v_lshlrev_b32_e32 v182, 2, v33
	v_or_b32_e32 v205, s36, v29
	s_or_b32 s57, s36, 31
	s_or_b32 s59, s6, 64
	v_or_b32_e32 v30, v30, v0
	s_mov_b64 s[0:1], 0xe600080
	v_or_b32_e32 v34, v34, v0
	s_add_u32 s54, s7, 0xce18000
	s_addc_u32 s55, 0, 0
	v_mov_b32_e32 v0, 0x180
	s_mov_b32 s62, 0
	v_mov_b32_e32 v203, 0
	v_mov_b32_e32 v204, 0xff800000
	s_mov_b32 s63, 0
	s_waitcnt vmcnt(16)
	ds_write_b128 v36, v[2:5]
	v_add3_u32 v2, 0, v209, v210
	s_waitcnt vmcnt(15)
	ds_write_b128 v2, v[6:9]
	v_add3_u32 v2, 0, v211, v212
	v_lshlrev_b32_e32 v3, 4, v33
	v_mov_b32_e32 v6, v1
	s_waitcnt vmcnt(14)
	ds_write_b128 v2, v[10:13]
	v_add3_u32 v2, v213, v214, s65
	v_mov_b32_e32 v7, v1
	v_mov_b32_e32 v8, v1
	v_mov_b32_e32 v9, v1
	s_waitcnt vmcnt(13)
	ds_write2_b64 v2, v[14:15], v[16:17] offset1:2
	v_add3_u32 v2, v213, v215, s65
	v_mov_b32_e32 v14, v1
	v_mov_b32_e32 v15, v1
	s_waitcnt vmcnt(12)
; DI void attn_unit(const Params& p, int b, int h, int qb, LAS unsigned char* lds, int tid, int lane, int wave) {
;     ...
;     int krow[3], kcol[3];
; #pragma unroll
;     for (int e = 0; e < 3; ++e) { const int c = tid + 512 * e; krow[e] = c / 24; kcol[e] = c % 24; }
;     u32x4 pk[3], pv[2];
	ds_write2_b64 v2, v[18:19], v[20:21] offset1:2
	v_or_b32_e32 v2, s56, v29
	v_mul_lo_u32 v2, v2, s77
	v_add3_u32 v216, 0, v2, v3
	v_mul_u32_u24_e32 v2, 0x90, v29
	v_lshlrev_b32_e32 v3, 2, v182
	v_lshl_add_u32 v3, s56, 1, v3
	v_add3_u32 v206, 0, v2, v3
	v_sub_u32_e32 v2, v205, v182
	v_subrev_u32_e32 v217, s56, v2
	v_lshl_add_u64 v[2:3], v[30:31], 0, s[92:93]
	v_lshl_add_u64 v[184:185], v[2:3], 0, s[0:1]
	v_lshl_add_u64 v[2:3], v[34:35], 0, s[92:93]
	v_lshl_add_u64 v[186:187], v[2:3], 0, s[0:1]
	v_mov_b64_e32 v[2:3], s[54:55]
	v_mad_i64_i32 v[4:5], s[0:1], v44, s76, v[2:3]
	v_mad_u64_u32 v[4:5], s[0:1], s2, v0, v[4:5]
	v_lshl_add_u64 v[188:189], v[4:5], 0, v[26:27]
	v_mad_i64_i32 v[4:5], s[0:1], v42, s76, v[2:3]
	v_mad_i64_i32 v[2:3], s[0:1], v40, s76, v[2:3]
	v_mad_u64_u32 v[4:5], s[0:1], s2, v0, v[4:5]
	v_mad_u64_u32 v[2:3], s[0:1], s2, v0, v[2:3]
	v_lshl_add_u64 v[190:191], v[4:5], 0, v[24:25]
	v_lshl_add_u64 v[192:193], v[2:3], 0, v[22:23]
	v_mov_b32_e32 v0, v1
	v_mov_b32_e32 v2, v1
	v_mov_b32_e32 v3, v1
	v_mov_b32_e32 v4, v1
	v_mov_b32_e32 v5, v1
	v_mov_b32_e32 v10, v1
	v_mov_b32_e32 v11, v1
	v_mov_b32_e32 v12, v1
	v_mov_b32_e32 v13, v1
	v_mov_b64_e32 v[64:65], v[14:15]
	v_mov_b64_e32 v[48:49], v[14:15]
	v_mov_b64_e32 v[32:33], v[14:15]
	v_mov_b64_e32 v[62:63], v[12:13]
	v_mov_b64_e32 v[60:61], v[10:11]
	v_mov_b64_e32 v[58:59], v[8:9]
	v_mov_b64_e32 v[56:57], v[6:7]
	v_mov_b64_e32 v[54:55], v[4:5]
	v_mov_b64_e32 v[52:53], v[2:3]
	v_mov_b64_e32 v[50:51], v[0:1]
	v_mov_b64_e32 v[46:47], v[12:13]
	v_mov_b64_e32 v[44:45], v[10:11]
	v_mov_b64_e32 v[42:43], v[8:9]
	v_mov_b64_e32 v[40:41], v[6:7]
	v_mov_b64_e32 v[38:39], v[4:5]
	v_mov_b64_e32 v[36:37], v[2:3]
	v_mov_b64_e32 v[34:35], v[0:1]
	v_mov_b64_e32 v[30:31], v[12:13]
	v_mov_b64_e32 v[28:29], v[10:11]
	v_mov_b64_e32 v[26:27], v[8:9]
	v_mov_b64_e32 v[24:25], v[6:7]
	v_mov_b64_e32 v[22:23], v[4:5]
	v_mov_b64_e32 v[20:21], v[2:3]
	v_mov_b64_e32 v[18:19], v[0:1]
	v_mov_b64_e32 v[16:17], v[14:15]
	v_mov_b64_e32 v[14:15], v[12:13]
	v_mov_b64_e32 v[12:13], v[10:11]
	v_mov_b64_e32 v[10:11], v[8:9]
	v_mov_b64_e32 v[8:9], v[6:7]
	v_mov_b64_e32 v[6:7], v[4:5]
	v_mov_b64_e32 v[4:5], v[2:3]
	v_mov_b64_e32 v[2:3], v[0:1]
	s_waitcnt lgkmcnt(0)
	s_barrier
	s_waitcnt vmcnt(0)
	v_lshl_add_u32 v222, s3, 6, v183
	v_and_b32_e32 v222, 0xff, v222
	s_movk_i32 s0, 0x600
	s_movk_i32 s1, 0x190
	s_cmp_lg_u32 s21, 0
	s_cbranch_scc1 .Lal1_b
	v_mov_b32_e32 v223, v222
	v_mul_u32_u24_e32 v224, 0xaaab, v223
	v_lshrrev_b32_e32 v224, 20, v224
	v_mul_u32_u24_e32 v225, 24, v224
	v_sub_u32_e32 v225, v223, v225
	v_lshlrev_b32_e32 v225, 4, v225
	v_mad_u32_u24 v230, v224, s0, v225
	v_mad_u32_u24 v237, v224, s1, v225
	v_add_u32_e32 v223, 256, v222
	v_mul_u32_u24_e32 v224, 0xaaab, v223
	v_lshrrev_b32_e32 v224, 20, v224
	v_mul_u32_u24_e32 v225, 24, v224
	v_sub_u32_e32 v225, v223, v225
	v_lshlrev_b32_e32 v225, 4, v225
	v_mad_u32_u24 v231, v224, s0, v225
	v_mad_u32_u24 v238, v224, s1, v225
	v_add_u32_e32 v223, 512, v222
	v_mul_u32_u24_e32 v224, 0xaaab, v223
	v_lshrrev_b32_e32 v224, 20, v224
	v_mul_u32_u24_e32 v225, 24, v224
	v_sub_u32_e32 v225, v223, v225
	v_lshlrev_b32_e32 v225, 4, v225
	v_mad_u32_u24 v232, v224, s0, v225
	v_mad_u32_u24 v239, v224, s1, v225
	v_add_u32_e32 v223, 768, v222
	v_mul_u32_u24_e32 v224, 0xaaab, v223
	v_lshrrev_b32_e32 v224, 20, v224
	v_mul_u32_u24_e32 v225, 24, v224
	v_sub_u32_e32 v225, v223, v225
	v_lshlrev_b32_e32 v225, 4, v225
	v_mad_u32_u24 v233, v224, s0, v225
	v_mad_u32_u24 v240, v224, s1, v225
	v_add_u32_e32 v223, 1024, v222
	v_mul_u32_u24_e32 v224, 0xaaab, v223
	v_lshrrev_b32_e32 v224, 20, v224
	v_mul_u32_u24_e32 v225, 24, v224
	v_sub_u32_e32 v225, v223, v225
	v_lshlrev_b32_e32 v225, 4, v225
	v_mad_u32_u24 v234, v224, s0, v225
	v_mad_u32_u24 v241, v224, s1, v225
	v_add_u32_e32 v223, 1280, v222
	v_mul_u32_u24_e32 v224, 0xaaab, v223
	v_lshrrev_b32_e32 v224, 20, v224
	v_mul_u32_u24_e32 v225, 24, v224
	v_sub_u32_e32 v225, v223, v225
	v_lshlrev_b32_e32 v225, 4, v225
	v_mad_u32_u24 v235, v224, s0, v225
	v_mad_u32_u24 v242, v224, s1, v225
	s_branch .Lal1_done
.Lal1_b:
	v_mov_b32_e32 v223, v222
	v_lshrrev_b32_e32 v224, 3, v223
	v_and_b32_e32 v225, 7, v223
	v_lshlrev_b32_e32 v230, 13, v224
	v_lshl_or_b32 v230, v225, 4, v230
	v_mul_u32_u24_e32 v224, 0x90, v224
	v_lshrrev_b32_e32 v223, 1, v225
	v_lshl_add_u32 v224, v223, 5, v224
	v_and_b32_e32 v225, 1, v225
	v_lshl_add_u32 v224, v225, 3, v224
	v_add_u32_e32 v236, 0xc800, v224
	v_add_u32_e32 v240, 0x11000, v224
	v_add_u32_e32 v223, 256, v222
	v_lshrrev_b32_e32 v224, 3, v223
	v_and_b32_e32 v225, 7, v223
	v_lshlrev_b32_e32 v231, 13, v224
	v_lshl_or_b32 v231, v225, 4, v231
	v_mul_u32_u24_e32 v224, 0x90, v224
	v_lshrrev_b32_e32 v223, 1, v225
	v_lshl_add_u32 v224, v223, 5, v224
	v_and_b32_e32 v225, 1, v225
	v_lshl_add_u32 v224, v225, 3, v224
	v_add_u32_e32 v237, 0xc800, v224
	v_add_u32_e32 v241, 0x11000, v224
	v_add_u32_e32 v223, 512, v222
	v_lshrrev_b32_e32 v224, 3, v223
	v_and_b32_e32 v225, 7, v223
	v_lshlrev_b32_e32 v232, 13, v224
	v_lshl_or_b32 v232, v225, 4, v232
	v_mul_u32_u24_e32 v224, 0x90, v224
	v_lshrrev_b32_e32 v223, 1, v225
	v_lshl_add_u32 v224, v223, 5, v224
	v_and_b32_e32 v225, 1, v225
	v_lshl_add_u32 v224, v225, 3, v224
	v_add_u32_e32 v238, 0xc800, v224
	v_add_u32_e32 v242, 0x11000, v224
	v_add_u32_e32 v223, 768, v222
	v_lshrrev_b32_e32 v224, 3, v223
	v_and_b32_e32 v225, 7, v223
	v_lshlrev_b32_e32 v233, 13, v224
	v_lshl_or_b32 v233, v225, 4, v233
	v_mul_u32_u24_e32 v224, 0x90, v224
	v_lshrrev_b32_e32 v223, 1, v225
	v_lshl_add_u32 v224, v223, 5, v224
	v_and_b32_e32 v225, 1, v225
	v_lshl_add_u32 v224, v225, 3, v224
	v_add_u32_e32 v239, 0xc800, v224
	v_add_u32_e32 v243, 0x11000, v224
.Lal1_done:
	s_mul_i32 s0, s66, 0x600
	s_mul_i32 s1, s2, 0x180
	s_add_u32 s0, s0, s1
	s_add_u32 s0, s0, 0xce18000
	s_add_u32 s98, s0, s50
	s_addc_u32 s99, 0, s51
	s_add_u32 s0, s92, 0xe600080
	s_add_u32 s100, s0, s50
	s_addc_u32 s101, 0, s51
	s_branch .LBB0_429

; #define LAS __attribute__((address_space(3)))
; #define MFMA32(a, b, c) __builtin_amdgcn_mfma_f32_32x32x16_bf16((a), (b), (c), 0, 0, 0)
; #define AT_LOAD(st) do { _Pragma("unroll") for (int e = 0; e < 3; ++e) pk[e] = *(const u32x4*)(kbase + (size_t)((st) * 64 + krow[e]) * 768 + kcol[e] * 8); \
;         _Pragma("unroll") for (int e = 0; e < 2; ++e) { const int c = tid + 512 * e; pv[e] = *(const u32x4*)(vbase + (size_t)(c >> 3) * SEQ + (st) * 64 + (c & 7) * 8); } } while (0)
; DI void attn_unit(const Params& p, int b, int h, int qb, LAS unsigned char* lds, int tid, int lane, int wave) {
;     ...
;     for (int st = 0; st < nst; ++st) {
;         const int buf = st & 1;
;         if (st + 1 < nst) AT_LOAD(st + 1);
;         const int kb = st * 64 + g * 32;
;         if (kb <= qr0 + 31) {
;             f32x16 s;
; #pragma unroll
;             for (int j = 0; j < 16; ++j) s[j] = 0.f;
;             const LAS unsigned char* kp = lds + AT_K0 + buf * AT_KB + (g * 32 + r) * 400 + hh * 16;
;             bf16x8 kf[12];
; #pragma unroll
;             for (int kk = 0; kk < 12; ++kk) kf[kk] = *(const LAS bf16x8*)(kp + kk * 32);
;             __builtin_amdgcn_sched_barrier(0);
;             __builtin_amdgcn_s_setprio(1);
; #pragma unroll
;             for (int kk = 0; kk < 12; ++kk) s = MFMA32(kf[kk], qf[kk], s);
;             __builtin_amdgcn_s_setprio(0);
;             const LAS unsigned char* vp = lds + AT_V0 + buf * AT_VB + r * 136 + (g * 32 + 4 * hh) * 2;
;             bf16x8 vf[2][4];
; #pragma unroll
;             for (int ks = 0; ks < 2; ++ks)
; #pragma unroll
;                 for (int blk = 0; blk < 4; ++blk) {
;                     const s16x4 lo = *(const LAS s16x4*)(vp + blk * 32 * 136 + ks * 32), hi = *(const LAS s16x4*)(vp + blk * 32 * 136 + ks * 32 + 16);
;                     vf[ks][blk] = __builtin_shufflevector(lo, hi, 0, 1, 2, 3, 4, 5, 6, 7);
;                 }
;             __builtin_amdgcn_sched_barrier(0);
;             if (kb + 31 > qr0) {
;                 const int qa = qr0 + r - kb - 4 * hh;
; #pragma unroll
;                 for (int j = 0; j < 16; ++j) if ((j & 3) + 8 * (j >> 2) > qa) s[j] = -INFINITY;
.LBB0_428:
	s_xor_b32 s0, s78, 1
	s_cmp_lg_u32 s21, 0
	s_cbranch_scc1 .Ld1_b
	s_cmp_eq_u32 s0, 0
	s_cbranch_scc1 .Ld1_a0
	s_waitcnt vmcnt(5)
	ds_write_b128 v237, v[130:133] offset:25600
	s_waitcnt vmcnt(4)
	ds_write_b128 v238, v[134:137] offset:25600
	s_waitcnt vmcnt(3)
	ds_write_b128 v239, v[138:141] offset:25600
	s_waitcnt vmcnt(2)
	ds_write_b128 v240, v[142:145] offset:25600
	s_waitcnt vmcnt(1)
	ds_write_b128 v241, v[146:149] offset:25600
	s_waitcnt vmcnt(0)
	ds_write_b128 v242, v[250:253] offset:25600
	s_branch .Ld1_join
.Ld1_a0:
	s_waitcnt vmcnt(5)
	ds_write_b128 v237, v[130:133]
	s_waitcnt vmcnt(4)
	ds_write_b128 v238, v[134:137]
	s_waitcnt vmcnt(3)
	ds_write_b128 v239, v[138:141]
	s_waitcnt vmcnt(2)
	ds_write_b128 v240, v[142:145]
	s_waitcnt vmcnt(1)
	ds_write_b128 v241, v[146:149]
	s_waitcnt vmcnt(0)
	ds_write_b128 v242, v[250:253]
	s_branch .Ld1_join
.Ld1_b:
	s_cmp_eq_u32 s0, 0
	s_cbranch_scc1 .Ld1_b0
	s_waitcnt vmcnt(3)
	ds_write2_b64 v240, v[130:131], v[132:133] offset1:2
	s_waitcnt vmcnt(2)
	ds_write2_b64 v241, v[134:135], v[136:137] offset1:2
	s_waitcnt vmcnt(1)
	ds_write2_b64 v242, v[138:139], v[140:141] offset1:2
	s_waitcnt vmcnt(0)
	ds_write2_b64 v243, v[142:143], v[144:145] offset1:2
	s_branch .Ld1_join
.Ld1_b0:
	s_waitcnt vmcnt(3)
	ds_write2_b64 v236, v[130:131], v[132:133] offset1:2
	s_waitcnt vmcnt(2)
	ds_write2_b64 v237, v[134:135], v[136:137] offset1:2
	s_waitcnt vmcnt(1)
	ds_write2_b64 v238, v[138:139], v[140:141] offset1:2
	s_waitcnt vmcnt(0)
	ds_write2_b64 v239, v[142:143], v[144:145] offset1:2
.Ld1_join:
	s_add_u32 s98, s98, 0x18000
	s_addc_u32 s99, s99, 0
	s_add_u32 s100, s100, 0x80
	s_addc_u32 s101, s101, 0
	s_add_i32 s62, s62, 64
	s_add_i32 s63, s63, 1
	v_subrev_u32_e32 v217, 64, v217
	s_cmp_eq_u32 s59, s62
	s_waitcnt lgkmcnt(0)
	s_barrier
	s_cbranch_scc1 .LBB0_434
.LBB0_429:
	s_cmp_lg_u32 s21, 0
	s_cbranch_scc1 .Lt1_na
	global_load_dwordx4 v[130:133], v230, s[98:99]
	global_load_dwordx4 v[134:137], v231, s[98:99]
	global_load_dwordx4 v[138:141], v232, s[98:99]
	global_load_dwordx4 v[142:145], v233, s[98:99]
	global_load_dwordx4 v[146:149], v234, s[98:99]
	global_load_dwordx4 v[250:253], v235, s[98:99]
.Lt1_na:
	s_cmp_lg_u32 s21, 1
	s_cbranch_scc1 .Lt1_nb
	global_load_dwordx4 v[130:133], v230, s[100:101]
	global_load_dwordx4 v[134:137], v231, s[100:101]
	global_load_dwordx4 v[138:141], v232, s[100:101]
	global_load_dwordx4 v[142:145], v233, s[100:101]
.Lt1_nb:
	s_and_b32 s78, s63, 1
	s_add_i32 s0, s56, s62
	s_cmp_gt_i32 s0, s57
	s_cbranch_scc1 .LBB0_428
	s_mul_i32 s1, s78, 0x6400
	v_add_u32_e32 v0, s1, v216
	ds_read_b128 v[66:69], v0
	ds_read_b128 v[150:153], v0 offset:32
	ds_read_b128 v[154:157], v0 offset:64
	ds_read_b128 v[158:161], v0 offset:96
	ds_read_b128 v[162:165], v0 offset:128
	ds_read_b128 v[166:169], v0 offset:160
	ds_read_b128 v[170:173], v0 offset:192
	ds_read_b128 v[174:177], v0 offset:224
	ds_read_b128 v[178:181], v0 offset:256
	ds_read_b128 v[194:197], v0 offset:288
	ds_read_b128 v[198:201], v0 offset:320
	ds_read_b128 v[218:221], v0 offset:352
	s_setprio 1
	s_setprio 0
	s_waitcnt lgkmcnt(11)
	v_mfma_f32_32x32x16_bf16 v[66:81], v[66:69], v[126:129], 0
	s_mul_i32 s1, s78, 0x4800
	v_add_u32_e32 v0, s1, v206
	s_waitcnt lgkmcnt(10)
	v_mfma_f32_32x32x16_bf16 v[66:81], v[150:153], v[122:125], v[66:81]
	s_waitcnt lgkmcnt(9)
	v_mfma_f32_32x32x16_bf16 v[66:81], v[154:157], v[118:121], v[66:81]
	s_waitcnt lgkmcnt(8)
	v_mfma_f32_32x32x16_bf16 v[66:81], v[158:161], v[114:117], v[66:81]
	s_waitcnt lgkmcnt(7)
	v_mfma_f32_32x32x16_bf16 v[66:81], v[162:165], v[110:113], v[66:81]
	s_waitcnt lgkmcnt(6)
	v_mfma_f32_32x32x16_bf16 v[66:81], v[166:169], v[106:109], v[66:81]
	ds_read_b128 v[166:169], v0 offset:51200
	ds_read_b128 v[150:153], v0 offset:51232
	s_waitcnt lgkmcnt(7)
	v_mfma_f32_32x32x16_bf16 v[66:81], v[170:173], v[102:105], v[66:81]
	ds_read_b128 v[170:173], v0 offset:55808
	s_waitcnt lgkmcnt(7)
	v_mfma_f32_32x32x16_bf16 v[66:81], v[174:177], v[98:101], v[66:81]
	s_waitcnt lgkmcnt(6)
	v_mfma_f32_32x32x16_bf16 v[66:81], v[178:181], v[94:97], v[66:81]
	ds_read_b128 v[178:181], v0 offset:60416
	ds_read_b128 v[174:177], v0 offset:65024
	ds_read_b128 v[162:165], v0 offset:55840
	ds_read_b128 v[158:161], v0 offset:60448
	ds_read_b128 v[154:157], v0 offset:65056
	s_waitcnt lgkmcnt(10)
	v_mfma_f32_32x32x16_bf16 v[66:81], v[194:197], v[90:93], v[66:81]
	s_waitcnt lgkmcnt(9)
	v_mfma_f32_32x32x16_bf16 v[66:81], v[198:201], v[86:89], v[66:81]
	s_waitcnt lgkmcnt(8)
	v_mfma_f32_32x32x16_bf16 v[66:81], v[218:221], v[82:85], v[66:81]
	s_add_i32 s0, s0, 31
	s_cmp_le_i32 s0, s36
	s_cbranch_scc1 .LBB0_432
	v_cmp_gt_i32_e64 s[30:31], 26, v217
	v_cmp_gt_i32_e64 s[34:35], 27, v217
	v_cmp_gt_i32_e64 s[28:29], 25, v217
	s_and_b64 s[30:31], s[34:35], s[30:31]
	v_cmp_gt_i32_e64 s[26:27], 24, v217
	s_and_b64 s[28:29], s[30:31], s[28:29]
	v_cmp_gt_i32_e64 s[24:25], 19, v217
	s_and_b64 s[26:27], s[28:29], s[26:27]
	v_cmp_gt_i32_e64 s[22:23], 18, v217
	s_and_b64 s[24:25], s[26:27], s[24:25]
	v_cmp_gt_i32_e64 s[18:19], 17, v217
	s_and_b64 s[22:23], s[24:25], s[22:23]
	v_cmp_gt_i32_e64 s[16:17], 16, v217
	s_and_b64 s[18:19], s[22:23], s[18:19]
	v_cmp_gt_i32_e64 s[14:15], 11, v217
	s_and_b64 s[16:17], s[18:19], s[16:17]
	v_cmp_gt_i32_e64 s[12:13], 10, v217
	s_and_b64 s[14:15], s[16:17], s[14:15]
	v_cmp_gt_i32_e64 s[10:11], 9, v217
	s_and_b64 s[12:13], s[14:15], s[12:13]
	v_cmp_gt_i32_e64 s[8:9], 8, v217
	s_and_b64 s[10:11], s[12:13], s[10:11]
	v_cmp_gt_i32_e64 s[6:7], 3, v217
	s_and_b64 s[8:9], s[10:11], s[8:9]
	v_cmp_gt_i32_e64 s[4:5], 2, v217
	s_and_b64 s[6:7], s[8:9], s[6:7]
	v_cmp_gt_i32_e64 s[0:1], 1, v217
	s_and_b64 s[4:5], s[6:7], s[4:5]
	v_cmp_gt_i32_e32 vcc, 0, v217
	s_and_b64 s[0:1], s[4:5], s[0:1]
	s_and_b64 vcc, s[0:1], vcc
	v_cndmask_b32_e64 v81, v81, v229, s[34:35]
	v_cndmask_b32_e64 v80, v80, v229, s[30:31]
	v_cndmask_b32_e64 v79, v79, v229, s[28:29]
	v_cndmask_b32_e64 v78, v78, v229, s[26:27]
	v_cndmask_b32_e64 v77, v77, v229, s[24:25]
	v_cndmask_b32_e64 v76, v76, v229, s[22:23]
	v_cndmask_b32_e64 v75, v75, v229, s[18:19]
	v_cndmask_b32_e64 v74, v74, v229, s[16:17]
	v_cndmask_b32_e64 v73, v73, v229, s[14:15]
	v_cndmask_b32_e64 v72, v72, v229, s[12:13]
	v_cndmask_b32_e64 v71, v71, v229, s[10:11]
	v_cndmask_b32_e64 v70, v70, v229, s[8:9]
	v_cndmask_b32_e64 v69, v69, v229, s[6:7]
	v_cndmask_b32_e64 v68, v68, v229, s[4:5]
	v_cndmask_b32_e64 v67, v67, v229, s[0:1]
	v_cndmask_b32_e32 v66, v66, v229, vcc

; #define LAS __attribute__((address_space(3)))
; #define AT_LOAD(st) do { _Pragma("unroll") for (int e = 0; e < 3; ++e) pk[e] = *(const u32x4*)(kbase + (size_t)((st) * 64 + krow[e]) * 768 + kcol[e] * 8); \
;         _Pragma("unroll") for (int e = 0; e < 2; ++e) { const int c = tid + 512 * e; pv[e] = *(const u32x4*)(vbase + (size_t)(c >> 3) * SEQ + (st) * 64 + (c & 7) * 8); } } while (0)
; DI void attn_unit(const Params& p, int b, int h, int qb, LAS unsigned char* lds, int tid, int lane, int wave) {
;     unsigned char* ws = p.ws;
;     const bf16_t* Q = (const bf16_t*)(ws + WS_QR); const bf16_t* KB = (const bf16_t*)(ws + WS_K); const bf16_t* VT = (const bf16_t*)(ws + WS_VT);
;     const bf16_t* Z = (const bf16_t*)(ws + WS_Z); bf16_t* OB = (bf16_t*)(ws + WS_KVR);
;     const int g = wave >> 2, w4 = wave & 3, r = lane & 31, hh = lane >> 5;
;     const int qr0 = qb * 128 + w4 * 32, nst = 2 * (qb + 1);
;     const size_t tokb = (size_t)b * SEQ;
;     bf16x8 qf[12];
;     { const bf16_t* qp = Q + (tokb + qr0 + r) * 768 + h * 192 + 8 * hh;
; #pragma unroll
;       for (int kk = 0; kk < 12; ++kk) qf[kk] = *(const bf16x8*)(qp + 16 * kk); }
;     f32x16 o[4];
; #pragma unroll
;     for (int i = 0; i < 4; ++i)
; #pragma unroll
;         for (int j = 0; j < 16; ++j) o[i][j] = 0.f;
;     float mrow = -INFINITY, lrow = 0.f;
;     const bf16_t* kbase = KB + tokb * 768 + h * 192;
;     const bf16_t* vbase = VT + (size_t)((b * 4 + h) * 128) * SEQ;
;     int krow[3], kcol[3];
; #pragma unroll
;     for (int e = 0; e < 3; ++e) { const int c = tid + 512 * e; krow[e] = c / 24; kcol[e] = c % 24; }
;     u32x4 pk[3], pv[2];
;     ...
;     AT_LOAD(0); AT_WRITE(0);
;     __syncthreads();
.LBB0_444:
	s_mov_b32 s3, s33
	s_mov_b64 s[0:1], s[50:51]
	s_barrier
	v_mbcnt_lo_u32_b32 v183, -1, 0
	v_mbcnt_hi_u32_b32 v183, -1, v183
	s_mov_b32 s0, 0x2aaaaaab
	v_lshl_add_u32 v14, s3, 6, v183
	v_mul_hi_i32 v0, v14, s0
	v_lshrrev_b32_e32 v2, 31, v0
	v_ashrrev_i32_e32 v0, 2, v0
	v_add_u32_e32 v40, v0, v2
	v_mul_lo_u32 v0, v40, 24
	v_add_u32_e32 v20, 0x200, v14
	v_sub_u32_e32 v41, v14, v0
	v_mul_hi_i32 v0, v20, s0
	v_lshrrev_b32_e32 v2, 31, v0
	v_ashrrev_i32_e32 v0, 2, v0
	v_add_u32_e32 v42, v0, v2
	v_mul_lo_u32 v0, v42, 24
	v_sub_u32_e32 v43, v20, v0
	v_add_u32_e32 v0, 0x400, v14
	v_mul_hi_i32 v2, v0, s0
	v_lshrrev_b32_e32 v3, 31, v2
	v_ashrrev_i32_e32 v2, 2, v2
	v_add_u32_e32 v44, v2, v3
	v_mul_lo_u32 v2, v44, 24
	v_sub_u32_e32 v45, v0, v2
	v_lshlrev_b32_e32 v4, 3, v41
	v_lshlrev_b32_e32 v6, 3, v43
	v_mov_b64_e32 v[10:11], s[52:53]
	v_ashrrev_i32_e32 v5, 31, v4
	v_ashrrev_i32_e32 v7, 31, v6
	v_lshlrev_b32_e32 v12, 3, v45
	v_mad_i64_i32 v[2:3], s[0:1], v40, s76, v[10:11]
	v_lshlrev_b64 v[22:23], 1, v[4:5]
	v_mad_i64_i32 v[4:5], s[0:1], v42, s76, v[10:11]
	v_lshlrev_b64 v[24:25], 1, v[6:7]
	v_ashrrev_i32_e32 v13, 31, v12
	v_lshlrev_b32_e32 v0, 4, v183
	v_ashrrev_i32_e32 v28, 3, v14
	v_lshl_add_u64 v[2:3], v[2:3], 0, v[22:23]
	v_lshl_add_u64 v[6:7], v[4:5], 0, v[24:25]
	v_mad_i64_i32 v[10:11], s[0:1], v44, s76, v[10:11]
	v_lshlrev_b64 v[26:27], 1, v[12:13]
	v_and_b32_e32 v0, 0x70, v0
	v_ashrrev_i32_e32 v29, 31, v28
	v_ashrrev_i32_e32 v32, 3, v20
	global_load_dwordx4 v[2:5], v[2:3], off
	s_nop 0
	global_load_dwordx4 v[6:9], v[6:7], off
	v_lshl_add_u64 v[10:11], v[10:11], 0, v[26:27]
	v_lshl_add_u64 v[18:19], s[74:75], 0, v[0:1]
	v_lshlrev_b64 v[30:31], 13, v[28:29]
	v_ashrrev_i32_e32 v33, 31, v32
	s_and_b32 s0, s72, 15
	s_and_b32 s20, s3, 3
	global_load_dwordx4 v[10:13], v[10:11], off
	v_lshl_add_u64 v[14:15], v[18:19], 0, v[30:31]
	v_lshlrev_b64 v[34:35], 13, v[32:33]
	s_lshl_b32 s4, s0, 7
	s_lshl_b32 s0, s94, 7
	s_lshl_b32 s5, s20, 5
	global_load_dwordx4 v[14:17], v[14:15], off
	v_lshl_add_u64 v[18:19], v[18:19], 0, v[34:35]
	v_and_b32_e32 v205, 31, v183
	s_or_b32 s36, s5, s0
	v_readlane_b32 s0, v254, 48
	global_load_dwordx4 v[18:21], v[18:19], off
	v_or_b32_e32 v33, s66, v205
	v_readlane_b32 s1, v254, 49
	v_or_b32_e32 v202, s36, v33
	v_ashrrev_i32_e32 v29, 5, v183
	v_mov_b64_e32 v[36:37], s[0:1]
	v_mad_u64_u32 v[36:37], s[0:1], v202, s76, v[36:37]
	s_lshl_b32 s0, s67, 1
	s_mov_b32 s1, s93
	v_lshlrev_b32_e32 v38, 3, v29
	v_lshl_add_u64 v[36:37], v[36:37], 0, s[0:1]
	v_ashrrev_i32_e32 v39, 31, v38
	v_lshl_add_u64 v[36:37], v[38:39], 1, v[36:37]
	global_load_dwordx4 v[126:129], v[36:37], off
	global_load_dwordx4 v[122:125], v[36:37], off offset:32
	global_load_dwordx4 v[118:121], v[36:37], off offset:64
	global_load_dwordx4 v[114:117], v[36:37], off offset:96
	global_load_dwordx4 v[110:113], v[36:37], off offset:128
	global_load_dwordx4 v[106:109], v[36:37], off offset:160
	global_load_dwordx4 v[102:105], v[36:37], off offset:192
	global_load_dwordx4 v[98:101], v[36:37], off offset:224
	global_load_dwordx4 v[94:97], v[36:37], off offset:256
	global_load_dwordx4 v[90:93], v[36:37], off offset:288
	global_load_dwordx4 v[86:89], v[36:37], off offset:320
	global_load_dwordx4 v[82:85], v[36:37], off offset:352
	v_mul_lo_u32 v207, v40, s77
	v_lshlrev_b32_e32 v208, 4, v41
	v_add3_u32 v33, 0, v207, v208
	v_mul_lo_u32 v209, v42, s77
	v_lshlrev_b32_e32 v210, 4, v43
	v_mul_lo_u32 v211, v44, s77
	v_lshlrev_b32_e32 v212, 4, v45
	s_movk_i32 s0, 0x90
	v_bfe_u32 v222, v0, 4, 1
	v_and_b32_e32 v213, 0x60, v0
	v_lshl_or_b32 v213, v222, 3, v213
	v_mul_lo_u32 v214, v28, s0
	s_ashr_i32 s21, s3, 2
	v_mul_lo_u32 v215, v32, s0
	s_lshl_b32 s53, s21, 5
	v_lshlrev_b32_e32 v182, 2, v29
	s_or_b32 s0, s4, s5
	v_or_b32_e32 v30, v30, v0
	v_or_b32_e32 v34, v34, v0
	s_or_b32 s52, s4, 64
	s_or_b32 s56, s36, 31
	v_mov_b32_e32 v0, v1
	v_mov_b32_e32 v203, 0
	v_mov_b32_e32 v204, 0xff800000
	s_waitcnt vmcnt(16)
	ds_write_b128 v33, v[2:5]
	v_add3_u32 v2, 0, v209, v210
	s_waitcnt vmcnt(15)
	ds_write_b128 v2, v[6:9]
	v_add3_u32 v2, 0, v211, v212
	v_lshlrev_b32_e32 v3, 4, v29
	v_mov_b32_e32 v6, v1
	v_mov_b32_e32 v7, v1
	v_mov_b32_e32 v8, v1
	s_waitcnt vmcnt(14)
	ds_write_b128 v2, v[10:13]
	v_add3_u32 v2, v213, v214, s65
	v_mov_b32_e32 v9, v1
	v_mov_b32_e32 v10, v1
	v_mov_b32_e32 v11, v1
	v_mov_b32_e32 v12, v1
	s_waitcnt vmcnt(13)
	ds_write2_b64 v2, v[14:15], v[16:17] offset1:2
	v_add3_u32 v2, v213, v215, s65
	v_mov_b32_e32 v14, v1
	v_mov_b32_e32 v15, v1
	v_mov_b32_e32 v13, v1
	s_waitcnt vmcnt(12)
	ds_write2_b64 v2, v[18:19], v[20:21] offset1:2
	v_or_b32_e32 v2, s53, v205
	v_mul_lo_u32 v2, v2, s77
	v_add3_u32 v216, 0, v2, v3
	v_mul_u32_u24_e32 v2, 0x90, v205
	v_lshlrev_b32_e32 v3, 2, v182
	v_lshl_add_u32 v3, s53, 1, v3
	v_add3_u32 v206, 0, v2, v3
	v_or_b32_e32 v2, s0, v205
	v_sub_u32_e32 v2, v2, v182
	v_subrev_u32_e32 v217, s53, v2
	v_lshl_add_u64 v[2:3], v[30:31], 0, s[92:93]
	s_mov_b64 s[0:1], 0xe600080
	v_lshl_add_u64 v[184:185], v[2:3], 0, s[0:1]
	v_lshl_add_u64 v[2:3], v[34:35], 0, s[92:93]
	v_lshl_add_u64 v[186:187], v[2:3], 0, s[0:1]
	s_mul_i32 s0, s2, 0x180
	s_add_u32 s0, s0, s54
	s_addc_u32 s1, 0, s55
	v_mov_b64_e32 v[2:3], s[0:1]
	v_mad_i64_i32 v[4:5], s[0:1], v44, s76, v[2:3]
	v_lshl_add_u64 v[188:189], v[4:5], 0, v[26:27]
	v_mad_i64_i32 v[4:5], s[0:1], v42, s76, v[2:3]
	v_mad_i64_i32 v[2:3], s[0:1], v40, s76, v[2:3]
	v_lshl_add_u64 v[190:191], v[4:5], 0, v[24:25]
	v_lshl_add_u64 v[192:193], v[2:3], 0, v[22:23]
	v_mov_b32_e32 v2, v1
	v_mov_b32_e32 v3, v1
	v_mov_b32_e32 v4, v1
	v_mov_b32_e32 v5, v1
	v_mov_b64_e32 v[64:65], v[14:15]
	v_mov_b64_e32 v[48:49], v[14:15]
	v_mov_b64_e32 v[32:33], v[14:15]
	v_mov_b64_e32 v[62:63], v[12:13]
	v_mov_b64_e32 v[60:61], v[10:11]
	v_mov_b64_e32 v[58:59], v[8:9]
	v_mov_b64_e32 v[56:57], v[6:7]
	v_mov_b64_e32 v[54:55], v[4:5]
	v_mov_b64_e32 v[52:53], v[2:3]
	v_mov_b64_e32 v[50:51], v[0:1]
	v_mov_b64_e32 v[46:47], v[12:13]
	v_mov_b64_e32 v[44:45], v[10:11]
	v_mov_b64_e32 v[42:43], v[8:9]
	v_mov_b64_e32 v[40:41], v[6:7]
	v_mov_b64_e32 v[38:39], v[4:5]
	v_mov_b64_e32 v[36:37], v[2:3]
	v_mov_b64_e32 v[34:35], v[0:1]
	v_mov_b64_e32 v[30:31], v[12:13]
	v_mov_b64_e32 v[28:29], v[10:11]
	v_mov_b64_e32 v[26:27], v[8:9]
	v_mov_b64_e32 v[24:25], v[6:7]
	v_mov_b64_e32 v[22:23], v[4:5]
	v_mov_b64_e32 v[20:21], v[2:3]
	v_mov_b64_e32 v[18:19], v[0:1]
	v_mov_b64_e32 v[16:17], v[14:15]
	s_mov_b32 s54, 0
	v_mov_b64_e32 v[14:15], v[12:13]
	v_mov_b64_e32 v[12:13], v[10:11]
	v_mov_b64_e32 v[10:11], v[8:9]
	v_mov_b64_e32 v[8:9], v[6:7]
	v_mov_b64_e32 v[6:7], v[4:5]
	v_mov_b64_e32 v[4:5], v[2:3]
	v_mov_b64_e32 v[2:3], v[0:1]
	s_mov_b32 s55, 0
	s_waitcnt lgkmcnt(0)
	s_barrier
; DI void attn_unit(const Params& p, int b, int h, int qb, LAS unsigned char* lds, int tid, int lane, int wave) {
;     ...
;     int krow[3], kcol[3];
; #pragma unroll
;     for (int e = 0; e < 3; ++e) { const int c = tid + 512 * e; krow[e] = c / 24; kcol[e] = c % 24; }
;     u32x4 pk[3], pv[2];
	s_waitcnt vmcnt(0)
	v_lshl_add_u32 v222, s3, 6, v183
	v_and_b32_e32 v222, 0xff, v222
	s_movk_i32 s0, 0x600
	s_movk_i32 s1, 0x190
	s_cmp_lg_u32 s21, 0
	s_cbranch_scc1 .Lal2_b
	v_mov_b32_e32 v223, v222
	v_mul_u32_u24_e32 v224, 0xaaab, v223
	v_lshrrev_b32_e32 v224, 20, v224
	v_mul_u32_u24_e32 v225, 24, v224
	v_sub_u32_e32 v225, v223, v225
	v_lshlrev_b32_e32 v225, 4, v225
	v_mad_u32_u24 v230, v224, s0, v225
	v_mad_u32_u24 v237, v224, s1, v225
	v_add_u32_e32 v223, 256, v222
	v_mul_u32_u24_e32 v224, 0xaaab, v223
	v_lshrrev_b32_e32 v224, 20, v224
	v_mul_u32_u24_e32 v225, 24, v224
	v_sub_u32_e32 v225, v223, v225
	v_lshlrev_b32_e32 v225, 4, v225
	v_mad_u32_u24 v231, v224, s0, v225
	v_mad_u32_u24 v238, v224, s1, v225
	v_add_u32_e32 v223, 512, v222
	v_mul_u32_u24_e32 v224, 0xaaab, v223
	v_lshrrev_b32_e32 v224, 20, v224
	v_mul_u32_u24_e32 v225, 24, v224
	v_sub_u32_e32 v225, v223, v225
	v_lshlrev_b32_e32 v225, 4, v225
	v_mad_u32_u24 v232, v224, s0, v225
	v_mad_u32_u24 v239, v224, s1, v225
	v_add_u32_e32 v223, 768, v222
	v_mul_u32_u24_e32 v224, 0xaaab, v223
	v_lshrrev_b32_e32 v224, 20, v224
	v_mul_u32_u24_e32 v225, 24, v224
	v_sub_u32_e32 v225, v223, v225
	v_lshlrev_b32_e32 v225, 4, v225
	v_mad_u32_u24 v233, v224, s0, v225
	v_mad_u32_u24 v240, v224, s1, v225
	v_add_u32_e32 v223, 1024, v222
	v_mul_u32_u24_e32 v224, 0xaaab, v223
	v_lshrrev_b32_e32 v224, 20, v224
	v_mul_u32_u24_e32 v225, 24, v224
	v_sub_u32_e32 v225, v223, v225
	v_lshlrev_b32_e32 v225, 4, v225
	v_mad_u32_u24 v234, v224, s0, v225
	v_mad_u32_u24 v241, v224, s1, v225
	v_add_u32_e32 v223, 1280, v222
	v_mul_u32_u24_e32 v224, 0xaaab, v223
	v_lshrrev_b32_e32 v224, 20, v224
	v_mul_u32_u24_e32 v225, 24, v224
	v_sub_u32_e32 v225, v223, v225
	v_lshlrev_b32_e32 v225, 4, v225
	v_mad_u32_u24 v235, v224, s0, v225
	v_mad_u32_u24 v242, v224, s1, v225
	s_branch .Lal2_done

.LBB0_446:
	s_xor_b32 s0, s57, 1
	s_cmp_lg_u32 s21, 0
	s_cbranch_scc1 .Ld2_b
	s_cmp_eq_u32 s0, 0
	s_cbranch_scc1 .Ld2_a0
	s_waitcnt vmcnt(5)
	ds_write_b128 v237, v[130:133] offset:25600
	s_waitcnt vmcnt(4)
	ds_write_b128 v238, v[134:137] offset:25600
	s_waitcnt vmcnt(3)
	ds_write_b128 v239, v[138:141] offset:25600
	s_waitcnt vmcnt(2)
	ds_write_b128 v240, v[142:145] offset:25600
	s_waitcnt vmcnt(1)
	ds_write_b128 v241, v[146:149] offset:25600
	s_waitcnt vmcnt(0)
	ds_write_b128 v242, v[250:253] offset:25600
	s_branch .Ld2_join

; #define AT_LOAD(st) do { _Pragma("unroll") for (int e = 0; e < 3; ++e) pk[e] = *(const u32x4*)(kbase + (size_t)((st) * 64 + krow[e]) * 768 + kcol[e] * 8); \
;         _Pragma("unroll") for (int e = 0; e < 2; ++e) { const int c = tid + 512 * e; pv[e] = *(const u32x4*)(vbase + (size_t)(c >> 3) * SEQ + (st) * 64 + (c & 7) * 8); } } while (0)
; DI void attn_unit(const Params& p, int b, int h, int qb, LAS unsigned char* lds, int tid, int lane, int wave) {
;     ...
;     for (int st = 0; st < nst; ++st) {
;         const int buf = st & 1;
;         if (st + 1 < nst) AT_LOAD(st + 1);
;     ...
;         if (st + 1 < nst) AT_WRITE(buf ^ 1);
;         __syncthreads();
.Ld2_join:
	s_add_u32 s98, s98, 0x18000
	s_addc_u32 s99, s99, 0
	s_add_u32 s100, s100, 0x80
	s_addc_u32 s101, s101, 0
	s_add_i32 s54, s54, 64
	s_add_i32 s55, s55, 1
	v_subrev_u32_e32 v217, 64, v217
	s_cmp_eq_u32 s52, s54
	s_waitcnt lgkmcnt(0)
	s_barrier
	s_cbranch_scc1 .LBB0_452

; #define LAS __attribute__((address_space(3)))
; #define MFMA32(a, b, c) __builtin_amdgcn_mfma_f32_32x32x16_bf16((a), (b), (c), 0, 0, 0)
; DI void attn_unit(const Params& p, int b, int h, int qb, LAS unsigned char* lds, int tid, int lane, int wave) {
;     ...
;         const int kb = st * 64 + g * 32;
;         if (kb <= qr0 + 31) {
;             f32x16 s;
; #pragma unroll
;             for (int j = 0; j < 16; ++j) s[j] = 0.f;
;             const LAS unsigned char* kp = lds + AT_K0 + buf * AT_KB + (g * 32 + r) * 400 + hh * 16;
;             bf16x8 kf[12];
; #pragma unroll
;             for (int kk = 0; kk < 12; ++kk) kf[kk] = *(const LAS bf16x8*)(kp + kk * 32);
;             __builtin_amdgcn_sched_barrier(0);
;             __builtin_amdgcn_s_setprio(1);
; #pragma unroll
;             for (int kk = 0; kk < 12; ++kk) s = MFMA32(kf[kk], qf[kk], s);
;             __builtin_amdgcn_s_setprio(0);
;             const LAS unsigned char* vp = lds + AT_V0 + buf * AT_VB + r * 136 + (g * 32 + 4 * hh) * 2;
;             bf16x8 vf[2][4];
; #pragma unroll
;             for (int ks = 0; ks < 2; ++ks)
; #pragma unroll
;                 for (int blk = 0; blk < 4; ++blk) {
;                     const s16x4 lo = *(const LAS s16x4*)(vp + blk * 32 * 136 + ks * 32), hi = *(const LAS s16x4*)(vp + blk * 32 * 136 + ks * 32 + 16);
;                     vf[ks][blk] = __builtin_shufflevector(lo, hi, 0, 1, 2, 3, 4, 5, 6, 7);
;                 }
;             __builtin_amdgcn_sched_barrier(0);
;             if (kb + 31 > qr0) {
;                 const int qa = qr0 + r - kb - 4 * hh;
; #pragma unroll
;                 for (int j = 0; j < 16; ++j) if ((j & 3) + 8 * (j >> 2) > qa) s[j] = -INFINITY;
.Lt2_nb:
	s_and_b32 s57, s55, 1
	s_add_i32 s0, s53, s54
	s_cmp_gt_i32 s0, s56
	s_cbranch_scc1 .LBB0_446
	s_mul_i32 s1, s57, 0x6400
	v_add_u32_e32 v0, s1, v216
	ds_read_b128 v[66:69], v0
	ds_read_b128 v[150:153], v0 offset:32
	ds_read_b128 v[154:157], v0 offset:64
	ds_read_b128 v[158:161], v0 offset:96
	ds_read_b128 v[162:165], v0 offset:128
	ds_read_b128 v[166:169], v0 offset:160
	ds_read_b128 v[170:173], v0 offset:192
	ds_read_b128 v[174:177], v0 offset:224
	ds_read_b128 v[178:181], v0 offset:256
	ds_read_b128 v[194:197], v0 offset:288
	ds_read_b128 v[198:201], v0 offset:320
	ds_read_b128 v[218:221], v0 offset:352
	s_setprio 1
	s_setprio 0
	s_waitcnt lgkmcnt(11)
	v_mfma_f32_32x32x16_bf16 v[66:81], v[66:69], v[126:129], 0
	s_mul_i32 s1, s57, 0x4800
	v_add_u32_e32 v0, s1, v206
	s_waitcnt lgkmcnt(10)
	v_mfma_f32_32x32x16_bf16 v[66:81], v[150:153], v[122:125], v[66:81]
	s_waitcnt lgkmcnt(9)
	v_mfma_f32_32x32x16_bf16 v[66:81], v[154:157], v[118:121], v[66:81]
	s_waitcnt lgkmcnt(8)
	v_mfma_f32_32x32x16_bf16 v[66:81], v[158:161], v[114:117], v[66:81]
	s_waitcnt lgkmcnt(7)
	v_mfma_f32_32x32x16_bf16 v[66:81], v[162:165], v[110:113], v[66:81]
	s_waitcnt lgkmcnt(6)
	v_mfma_f32_32x32x16_bf16 v[66:81], v[166:169], v[106:109], v[66:81]
	ds_read_b128 v[166:169], v0 offset:51200
	ds_read_b128 v[150:153], v0 offset:51232
	s_waitcnt lgkmcnt(7)
	v_mfma_f32_32x32x16_bf16 v[66:81], v[170:173], v[102:105], v[66:81]
	ds_read_b128 v[170:173], v0 offset:55808
	s_waitcnt lgkmcnt(7)
	v_mfma_f32_32x32x16_bf16 v[66:81], v[174:177], v[98:101], v[66:81]
	s_waitcnt lgkmcnt(6)
	v_mfma_f32_32x32x16_bf16 v[66:81], v[178:181], v[94:97], v[66:81]
	ds_read_b128 v[178:181], v0 offset:60416
	ds_read_b128 v[174:177], v0 offset:65024
	ds_read_b128 v[162:165], v0 offset:55840
	ds_read_b128 v[158:161], v0 offset:60448
	ds_read_b128 v[154:157], v0 offset:65056
	s_waitcnt lgkmcnt(10)
	v_mfma_f32_32x32x16_bf16 v[66:81], v[194:197], v[90:93], v[66:81]
	s_waitcnt lgkmcnt(9)
	v_mfma_f32_32x32x16_bf16 v[66:81], v[198:201], v[86:89], v[66:81]
	s_waitcnt lgkmcnt(8)
	v_mfma_f32_32x32x16_bf16 v[66:81], v[218:221], v[82:85], v[66:81]
	s_add_i32 s0, s0, 31
	s_cmp_le_i32 s0, s36
	s_cbranch_scc1 .LBB0_450
	v_cmp_gt_i32_e64 s[30:31], 26, v217
	v_cmp_gt_i32_e64 s[34:35], 27, v217
	v_cmp_gt_i32_e64 s[28:29], 25, v217
	s_and_b64 s[30:31], s[34:35], s[30:31]
	v_cmp_gt_i32_e64 s[26:27], 24, v217
	s_and_b64 s[28:29], s[30:31], s[28:29]
	v_cmp_gt_i32_e64 s[24:25], 19, v217
	s_and_b64 s[26:27], s[28:29], s[26:27]
	v_cmp_gt_i32_e64 s[22:23], 18, v217
	s_and_b64 s[24:25], s[26:27], s[24:25]
	v_cmp_gt_i32_e64 s[18:19], 17, v217
	s_and_b64 s[22:23], s[24:25], s[22:23]
	v_cmp_gt_i32_e64 s[16:17], 16, v217
	s_and_b64 s[18:19], s[22:23], s[18:19]
	v_cmp_gt_i32_e64 s[14:15], 11, v217
	s_and_b64 s[16:17], s[18:19], s[16:17]
	v_cmp_gt_i32_e64 s[12:13], 10, v217
	s_and_b64 s[14:15], s[16:17], s[14:15]
	v_cmp_gt_i32_e64 s[10:11], 9, v217
	s_and_b64 s[12:13], s[14:15], s[12:13]
	v_cmp_gt_i32_e64 s[8:9], 8, v217
	s_and_b64 s[10:11], s[12:13], s[10:11]
	v_cmp_gt_i32_e64 s[6:7], 3, v217
	s_and_b64 s[8:9], s[10:11], s[8:9]
	v_cmp_gt_i32_e64 s[4:5], 2, v217
	s_and_b64 s[6:7], s[8:9], s[6:7]
	v_cmp_gt_i32_e64 s[0:1], 1, v217
	s_and_b64 s[4:5], s[6:7], s[4:5]
	v_cmp_gt_i32_e32 vcc, 0, v217
	s_and_b64 s[0:1], s[4:5], s[0:1]
	s_and_b64 vcc, s[0:1], vcc
	v_cndmask_b32_e64 v81, v81, v229, s[34:35]
	v_cndmask_b32_e64 v80, v80, v229, s[30:31]
	v_cndmask_b32_e64 v79, v79, v229, s[28:29]
	v_cndmask_b32_e64 v78, v78, v229, s[26:27]
	v_cndmask_b32_e64 v77, v77, v229, s[24:25]
	v_cndmask_b32_e64 v76, v76, v229, s[22:23]
	v_cndmask_b32_e64 v75, v75, v229, s[18:19]
	v_cndmask_b32_e64 v74, v74, v229, s[16:17]
	v_cndmask_b32_e64 v73, v73, v229, s[14:15]
	v_cndmask_b32_e64 v72, v72, v229, s[12:13]
	v_cndmask_b32_e64 v71, v71, v229, s[10:11]
	v_cndmask_b32_e64 v70, v70, v229, s[8:9]
	v_cndmask_b32_e64 v69, v69, v229, s[6:7]
	v_cndmask_b32_e64 v68, v68, v229, s[4:5]
	v_cndmask_b32_e64 v67, v67, v229, s[0:1]
	v_cndmask_b32_e32 v66, v66, v229, vcc

; __global__ void __launch_bounds__(512, 2) hymba_fwd(Params p) {
	.amdhsa_kernel _Z9hymba_fwd6Params
		.amdhsa_group_segment_fixed_size 0
		.amdhsa_private_segment_fixed_size 0
		.amdhsa_kernarg_size 384
		.amdhsa_user_sgpr_count 2
		.amdhsa_user_sgpr_dispatch_ptr 0
		.amdhsa_user_sgpr_queue_ptr 0
		.amdhsa_user_sgpr_kernarg_segment_ptr 1
		.amdhsa_user_sgpr_dispatch_id 0
		.amdhsa_user_sgpr_kernarg_preload_length 0
		.amdhsa_user_sgpr_kernarg_preload_offset 0
		.amdhsa_user_sgpr_private_segment_size 0
		.amdhsa_uses_dynamic_stack 0
		.amdhsa_enable_private_segment 0
		.amdhsa_system_sgpr_workgroup_id_x 1
		.amdhsa_system_sgpr_workgroup_id_y 0
		.amdhsa_system_sgpr_workgroup_id_z 0
		.amdhsa_system_sgpr_workgroup_info 0
		.amdhsa_system_vgpr_workitem_id 2
		.amdhsa_next_free_vgpr 256
		.amdhsa_next_free_sgpr 102
		.amdhsa_accum_offset 256
		.amdhsa_reserve_vcc 1
		.amdhsa_float_round_mode_32 0
		.amdhsa_float_round_mode_16_64 0
		.amdhsa_float_denorm_mode_32 3
		.amdhsa_float_denorm_mode_16_64 3
		.amdhsa_dx10_clamp 1
		.amdhsa_ieee_mode 1
		.amdhsa_fp16_overflow 0
		.amdhsa_tg_split 0
		.amdhsa_exception_fp_ieee_invalid_op 0
		.amdhsa_exception_fp_denorm_src 0
		.amdhsa_exception_fp_ieee_div_zero 0
		.amdhsa_exception_fp_ieee_overflow 0
		.amdhsa_exception_fp_ieee_underflow 0
		.amdhsa_exception_fp_ieee_inexact 0
		.amdhsa_exception_int_div_zero 0
	.end_amdhsa_kernel

; __global__ void __launch_bounds__(512, 2) hymba_fwd(Params p) {
amdhsa.kernels:
  - .agpr_count:     0
    .args:
      - .offset:         0
        .size:           128
        .value_kind:     by_value
      - .offset:         128
        .size:           4
        .value_kind:     hidden_block_count_x
      - .offset:         132
        .size:           4
        .value_kind:     hidden_block_count_y
      - .offset:         136
        .size:           4
        .value_kind:     hidden_block_count_z
      - .offset:         140
        .size:           2
        .value_kind:     hidden_group_size_x
      - .offset:         142
        .size:           2
        .value_kind:     hidden_group_size_y
      - .offset:         144
        .size:           2
        .value_kind:     hidden_group_size_z
      - .offset:         146
        .size:           2
        .value_kind:     hidden_remainder_x
      - .offset:         148
        .size:           2
        .value_kind:     hidden_remainder_y
      - .offset:         150
        .size:           2
        .value_kind:     hidden_remainder_z
      - .offset:         168
        .size:           8
        .value_kind:     hidden_global_offset_x
      - .offset:         176
        .size:           8
        .value_kind:     hidden_global_offset_y
      - .offset:         184
        .size:           8
        .value_kind:     hidden_global_offset_z
      - .offset:         192
        .size:           2
        .value_kind:     hidden_grid_dims
      - .offset:         216
        .size:           8
        .value_kind:     hidden_multigrid_sync_arg
      - .offset:         248
        .size:           4
        .value_kind:     hidden_dynamic_lds_size
    .group_segment_fixed_size: 0
    .kernarg_segment_align: 8
    .kernarg_segment_size: 384
    .language:       OpenCL C
    .language_version:
      - 2
      - 0
    .max_flat_workgroup_size: 512
    .name:           _Z9hymba_fwd6Params
    .private_segment_fixed_size: 0
    .sgpr_count:     108
    .sgpr_spill_count: 118
    .symbol:         _Z9hymba_fwd6Params.kd
    .uniform_work_group_size: 1
    .uses_dynamic_stack: false
    .vgpr_count:     256
    .vgpr_spill_count: 0
    .wavefront_size: 64
